# ATTN k-loop lazy rescale: running max moves per lane only when it grows by >8 log2 units; O rescale skipped when no lane with finite max moves
# speedup vs baseline: 1.0116x; 1.0116x over previous
.LBB0_1465:
	v_lshrrev_b32_e32 v0, s40, v104
	v_and_b32_e32 v0, 1, v0
	v_cmp_eq_u32_e32 vcc, 1, v0
	s_or_b64 s[0:1], s[0:1], vcc
	v_cndmask_b32_e64 v0, v211, v129, s[0:1]
	ds_bpermute_b32 v1, v155, v0
	v_add_u32_e32 v252, s37, v204
	ds_read_b64_tr_b16 v[236:237], v252 offset:18432
	ds_read_b64_tr_b16 v[238:239], v252 offset:19584
	ds_read_b64_tr_b16 v[240:241], v252 offset:18496
	ds_read_b64_tr_b16 v[242:243], v252 offset:19648
	ds_read_b64_tr_b16 v[244:245], v252 offset:20736
	ds_read_b64_tr_b16 v[246:247], v252 offset:21888
	ds_read_b64_tr_b16 v[248:249], v252 offset:20800
	ds_read_b64_tr_b16 v[250:251], v252 offset:21952
	s_mov_b64 s[2:3], -1
	s_waitcnt lgkmcnt(8)
	v_max3_f32 v33, v123, v0, v1
	v_sub_f32_e32 v253, v33, v123
	v_cmp_neq_f32_e64 s[98:99], s70, v123
	v_cmp_lt_f32_e32 vcc, 0x41000000, v253
	s_nop 1
	v_cndmask_b32_e32 v33, v123, v33, vcc
	v_cmp_neq_f32_e32 vcc, s70, v33
	s_nop 1
	v_cndmask_b32_e32 v125, 0, v33, vcc
	v_cndmask_b32_e64 v253, v212, v125, s[0:1]
	v_sub_f32_e32 v0, v38, v253
	v_sub_f32_e32 v1, v39, v253
	v_sub_f32_e32 v2, v36, v253
	v_sub_f32_e32 v3, v37, v253
	v_sub_f32_e32 v4, v40, v253
	v_sub_f32_e32 v5, v41, v253
	v_sub_f32_e32 v6, v34, v253
	v_sub_f32_e32 v7, v35, v253
	v_sub_f32_e32 v8, v134, v253
	v_sub_f32_e32 v9, v135, v253
	v_sub_f32_e32 v10, v44, v253
	v_sub_f32_e32 v11, v45, v253
	v_sub_f32_e32 v12, v46, v253
	v_sub_f32_e32 v13, v47, v253
	v_sub_f32_e32 v14, v42, v253
	v_sub_f32_e32 v15, v43, v253
	v_sub_f32_e32 v16, v142, v253
	v_sub_f32_e32 v17, v143, v253
	v_sub_f32_e32 v18, v138, v253
	v_sub_f32_e32 v19, v139, v253
	v_sub_f32_e32 v20, v140, v253
	v_sub_f32_e32 v21, v141, v253
	v_sub_f32_e32 v22, v136, v253
	v_sub_f32_e32 v23, v137, v253
	v_sub_f32_e32 v24, v150, v253
	v_sub_f32_e32 v25, v151, v253
	v_sub_f32_e32 v26, v146, v253
	v_sub_f32_e32 v27, v147, v253
	v_sub_f32_e32 v28, v148, v253
	v_sub_f32_e32 v29, v149, v253
	v_sub_f32_e32 v30, v144, v253
	v_sub_f32_e32 v31, v145, v253
	v_sub_f32_e32 v34, v123, v125
	v_exp_f32_e32 v34, v34
	s_waitcnt lgkmcnt(6)
	ds_read_b64_tr_b16 v[134:135], v252 offset:23040
	ds_read_b64_tr_b16 v[136:137], v252 offset:24192
	ds_read_b64_tr_b16 v[138:139], v252 offset:23104
	ds_read_b64_tr_b16 v[140:141], v252 offset:24256
	ds_read_b64_tr_b16 v[142:143], v252 offset:25344
	ds_read_b64_tr_b16 v[144:145], v252 offset:26496
	ds_read_b64_tr_b16 v[146:147], v252 offset:25408
	ds_read_b64_tr_b16 v[148:149], v252 offset:26560
	v_cmp_neq_f32_e32 vcc, 1.0, v34
	v_mov_b32_e32 v37, 0
	s_and_b64 vcc, vcc, s[98:99]
	s_cbranch_vccz .Lfa_norescale2
	v_mul_f32_e32 v78, v34, v78
	v_mul_f32_e32 v79, v34, v79
	v_mul_f32_e32 v76, v34, v76
	v_mul_f32_e32 v77, v34, v77
	v_mul_f32_e32 v74, v34, v74
	v_mul_f32_e32 v75, v34, v75
	v_mul_f32_e32 v72, v34, v72
	v_mul_f32_e32 v73, v34, v73
	v_mul_f32_e32 v70, v34, v70
	v_mul_f32_e32 v71, v34, v71
	v_mul_f32_e32 v68, v34, v68
	v_mul_f32_e32 v69, v34, v69
	v_mul_f32_e32 v66, v34, v66
	v_mul_f32_e32 v67, v34, v67
	v_mul_f32_e32 v64, v34, v64
	v_mul_f32_e32 v65, v34, v65
	v_mul_f32_e32 v62, v34, v62
	v_mul_f32_e32 v63, v34, v63
	v_mul_f32_e32 v60, v34, v60
	v_mul_f32_e32 v61, v34, v61
	v_mul_f32_e32 v58, v34, v58
	v_mul_f32_e32 v59, v34, v59
	v_mul_f32_e32 v56, v34, v56
	v_mul_f32_e32 v57, v34, v57
	v_mul_f32_e32 v54, v34, v54
	v_mul_f32_e32 v55, v34, v55
	v_mul_f32_e32 v52, v34, v52
	v_mul_f32_e32 v53, v34, v53
	v_mul_f32_e32 v50, v34, v50
	v_mul_f32_e32 v51, v34, v51
	v_mul_f32_e32 v48, v34, v48
	v_mul_f32_e32 v49, v34, v49

.Lfa_fast:
	v_mov_b32_e32 v33, s69
	ds_read_b32 v127, v33 offset:764
	v_max_f32_e32 v252, v0, v1
	v_max3_f32 v252, v252, v2, v3
	v_max3_f32 v252, v252, v4, v5
	v_max3_f32 v252, v252, v6, v7
	v_max3_f32 v252, v252, v8, v9
	v_max3_f32 v252, v252, v10, v11
	v_max3_f32 v252, v252, v12, v13
	v_max3_f32 v252, v252, v14, v15
	v_max3_f32 v252, v252, v16, v17
	v_max3_f32 v252, v252, v18, v19
	v_max3_f32 v252, v252, v20, v21
	v_max3_f32 v252, v252, v22, v23
	v_max3_f32 v252, v252, v24, v25
	v_max3_f32 v252, v252, v26, v27
	v_max3_f32 v252, v252, v28, v29
	v_max3_f32 v252, v252, v30, v31
	v_lshrrev_b32_e32 v253, s40, v104
	v_and_b32_e32 v253, 1, v253
	v_cmp_eq_u32_e32 vcc, 1, v253
	s_or_b64 s[0:1], s[0:1], vcc
	s_waitcnt lgkmcnt(0)
	v_fmamk_f32 v129, v252, 0x3fb8aa3b, v127
	v_cndmask_b32_e64 v252, v211, v129, s[0:1]
	ds_bpermute_b32 v253, v155, v252
	v_add_u32_e32 v47, s37, v204
	ds_read_b64_tr_b16 v[134:135], v47 offset:18432
	ds_read_b64_tr_b16 v[136:137], v47 offset:19584
	ds_read_b64_tr_b16 v[138:139], v47 offset:18496
	ds_read_b64_tr_b16 v[140:141], v47 offset:19648
	ds_read_b64_tr_b16 v[142:143], v47 offset:20736
	ds_read_b64_tr_b16 v[144:145], v47 offset:21888
	ds_read_b64_tr_b16 v[146:147], v47 offset:20800
	ds_read_b64_tr_b16 v[148:149], v47 offset:21952
	s_waitcnt lgkmcnt(8)
	v_max3_f32 v33, v123, v252, v253
	v_sub_f32_e32 v34, v33, v123
	v_cmp_neq_f32_e64 s[98:99], s70, v123
	v_cmp_lt_f32_e32 vcc, 0x41000000, v34
	v_mov_b32_e32 v37, 0
	s_nop 0
	v_cndmask_b32_e32 v33, v123, v33, vcc
	v_cmp_neq_f32_e32 vcc, s70, v33
	s_nop 1
	v_cndmask_b32_e32 v125, 0, v33, vcc
	v_sub_f32_e32 v252, v127, v125
	v_cndmask_b32_e64 v36, v211, v252, s[0:1]
	v_sub_f32_e32 v34, v123, v125
	v_exp_f32_e32 v34, v34
	s_waitcnt lgkmcnt(6)
	ds_read_b64_tr_b16 v[236:237], v47 offset:23040
	ds_read_b64_tr_b16 v[238:239], v47 offset:24192
	ds_read_b64_tr_b16 v[240:241], v47 offset:23104
	ds_read_b64_tr_b16 v[242:243], v47 offset:24256
	ds_read_b64_tr_b16 v[244:245], v47 offset:25344
	ds_read_b64_tr_b16 v[246:247], v47 offset:26496
	ds_read_b64_tr_b16 v[248:249], v47 offset:25408
	ds_read_b64_tr_b16 v[250:251], v47 offset:26560
	v_cmp_neq_f32_e32 vcc, 1.0, v34
	s_nop 0
	s_and_b64 vcc, vcc, s[98:99]
	s_cbranch_vccz .Lfa_norescale
	v_mul_f32_e32 v78, v34, v78
	v_mul_f32_e32 v79, v34, v79
	v_mul_f32_e32 v76, v34, v76
	v_mul_f32_e32 v77, v34, v77
	v_mul_f32_e32 v74, v34, v74
	v_mul_f32_e32 v75, v34, v75
	v_mul_f32_e32 v72, v34, v72
	v_mul_f32_e32 v73, v34, v73
	v_mul_f32_e32 v70, v34, v70
	v_mul_f32_e32 v71, v34, v71
	v_mul_f32_e32 v68, v34, v68
	v_mul_f32_e32 v69, v34, v69
	v_mul_f32_e32 v66, v34, v66
	v_mul_f32_e32 v67, v34, v67
	v_mul_f32_e32 v64, v34, v64
	v_mul_f32_e32 v65, v34, v65
	v_mul_f32_e32 v62, v34, v62
	v_mul_f32_e32 v63, v34, v63
	v_mul_f32_e32 v60, v34, v60
	v_mul_f32_e32 v61, v34, v61
	v_mul_f32_e32 v58, v34, v58
	v_mul_f32_e32 v59, v34, v59
	v_mul_f32_e32 v56, v34, v56
	v_mul_f32_e32 v57, v34, v57
	v_mul_f32_e32 v54, v34, v54
	v_mul_f32_e32 v55, v34, v55
	v_mul_f32_e32 v52, v34, v52
	v_mul_f32_e32 v53, v34, v53
	v_mul_f32_e32 v50, v34, v50
	v_mul_f32_e32 v51, v34, v51
	v_mul_f32_e32 v48, v34, v48
	v_mul_f32_e32 v49, v34, v49
